# P2 task split rebalanced after class-restricted duration probes showed non-owner workgroups finish ~30us after GEMM-unit owners: owners take 9 prompt tasks (8 in the last layer) instead of 8 (6)
# baseline (speedup 1.0000x reference)
; __device__ __forceinline__ void p2_phase(LAS unsigned char* lds, const Params& p, int l, int tid, int wave, int lane, int bid, int G) {
;     ...
;     const int ngemm = (l < DEPTH - 1) ? 120 : 32;
;     int start, count;
;     const int xg = (l < DEPTH - 1) ? 8 : 6;
;     if (bid < ngemm) { start = bid * xg; count = xg; }
;     else { const int rest = 3072 - ngemm * xg, nb = 256 - ngemm, q = rest / nb, rem = rest - q * nb, j = bid - ngemm; start = ngemm * xg + j * q + (j < rem ? j : rem); count = q + (j < rem ? 1 : 0); }
;     const int end = start + count;
;     const int ta0 = 2 * (start / 3) + (start % 3 < 2 ? start % 3 : 2), ta1 = 2 * (end / 3) + (end % 3 < 2 ? end % 3 : 2), ug0 = start / 3, ug1 = end / 3;
.LBB0_318:
	s_or_b64 exec, exec, s[0:1]
	v_readlane_b32 s0, v255, 13
	v_readlane_b32 s1, v255, 14
	s_cmp_eq_u32 s0, 3
	s_cselect_b64 s[0:1], -1, 0
	s_and_b64 s[10:11], s[0:1], exec
	s_cselect_b32 s7, 32, 0x78
	s_cmp_ge_i32 s2, s7
	s_cselect_b64 s[38:39], -1, 0
	s_mov_b64 s[10:11], -1
	s_and_b64 vcc, exec, s[38:39]
	s_cbranch_vccnz .LBB0_320
	s_and_b64 s[10:11], s[0:1], exec
	s_cselect_b32 s13, 8, 9
	s_mul_i32 s12, s13, s2
	s_mov_b64 s[10:11], 0
.LBB0_320:
	s_andn2_b64 vcc, exec, s[10:11]
	s_cbranch_vccnz .LBB0_322
	s_and_b64 s[0:1], s[0:1], exec
	s_movk_i32 s0, 0x438
	s_cselect_b32 s10, 0x100, s0
	s_sub_i32 s12, 0x100, s7
	v_cvt_f32_u32_e32 v2, s12
	s_sub_i32 s11, 0xc00, s10
	v_cvt_f32_u32_e32 v0, s11
	v_rcp_iflag_f32_e32 v3, v2
	s_nop 0
	v_mul_f32_e32 v3, v0, v3
	v_trunc_f32_e32 v3, v3
	v_fma_f32 v0, -v3, v2, v0
	v_cvt_u32_f32_e32 v3, v3
	v_cmp_ge_f32_e64 s[0:1], |v0|, v2
	s_cmp_lg_u64 s[0:1], 0
	v_readfirstlane_b32 s13, v3
	s_addc_u32 s0, s13, 0
	s_and_b32 s13, s0, 0xfff
	s_sub_i32 s7, s2, s7
	s_mul_i32 s12, s12, s13
	s_mul_i32 s0, s7, s13
	s_sub_i32 s11, s11, s12
	s_add_i32 s10, s0, s10
	s_cmp_lt_i32 s7, s11
	s_cselect_b64 s[0:1], -1, 0
	s_min_i32 s7, s7, s11
	s_add_i32 s12, s10, s7
	s_cmp_lg_u64 s[0:1], 0
	s_addc_u32 s13, s13, 0
